# M3: placement: first K-loop MFMA run shifted to 4 mod 8 (two s_nop 0), rest of the loop at its P16 byte phase
# speedup vs baseline: 1.0144x; 1.0144x over previous
; #define PG8_STAGE(bufoff, gbase, voff) do { _Pragma("unroll") for (int _i = 0; _i < 2; ++_i) { unsigned _vo = (voff)[_i]; asm volatile("" : "+v"(_vo));   \
;         __builtin_amdgcn_global_load_lds((const unsigned*)((const char*)(gbase) + _vo), (LAS unsigned*)(lds + (bufoff) + ldsw + _i * 8192), 16, 0, 0); } } while (0)
; #define PG8_LDA(dst, b, h) do { _Pragma("unroll") for (int m = 0; m < 4; ++m) _Pragma("unroll") for (int k = 0; k < 2; ++k) dst[m][k] = *(const LAS bf16x8*)(lds + PG8_SA(b, h) + aoff + m * 2048 + k * 1024); } while (0)
; #define PG8_LDB(dst, b, h) do { _Pragma("unroll") for (int n = 0; n < 2; ++n) _Pragma("unroll") for (int k = 0; k < 2; ++k) dst[n][k] = *(const LAS bf16x8*)(lds + PG8_SB(b, h) + boff + n * 2048 + k * 1024); } while (0)
; #define PG8_MMA(ai, bj, At, Bt) do { __builtin_amdgcn_s_setprio(1); _Pragma("unroll") for (int m = 0; m < 4; ++m) _Pragma("unroll") for (int n = 0; n < 2; ++n) _Pragma("unroll") for (int k = 0; k < 2; ++k) \
;         acc[ai][bj][m][n] = __builtin_amdgcn_mfma_f32_16x16x32_bf16(Bt[n][k], At[m][k], acc[ai][bj][m][n], 0, 0, 0); __builtin_amdgcn_s_setprio(0); } while (0)
; #define PG8_WAIT_V(n) asm volatile("s_waitcnt vmcnt(" #n ")" ::: "memory")
; #define PG8_WAIT_L(n) asm volatile("s_waitcnt lgkmcnt(" #n ")" ::: "memory")
; #define PG8_BAR __builtin_amdgcn_s_barrier()
; #define PG8_SCHED __builtin_amdgcn_sched_barrier(0)
; __device__ __forceinline__ void gemm_phase(LAS unsigned char* lds, const Call& C, const int tid, const Args& args) {
;     ...
;             PG8_LDB(B0, 0, 0); PG8_LDB(B1, 0, 1); PG8_SCHED; PG8_LDA(At, 0, 0); PG8_STAGE(PG8_SA(1, 1), a1 + hstepA, voffA);
;             PG8_WAIT_V(8); PG8_WAIT_L(0); PG8_BAR; PG8_MMA(0, 0, At, B0); PG8_MMA(0, 1, At, B1); PG8_BAR; PG8_SCHED;
;             PG8_LDA(At, 0, 1); PG8_STAGE(PG8_SB(0, 0), b2, voffB); PG8_STAGE(PG8_SB(0, 1), b2 + hstepB, voffB); PG8_STAGE(PG8_SA(0, 0), a2, voffA);
;             PG8_WAIT_V(8); PG8_WAIT_L(0); PG8_BAR; PG8_MMA(1, 0, At, B0); PG8_MMA(1, 1, At, B1); PG8_BAR; PG8_SCHED;
.Lnu_nofetch:
	s_add_i32 s25, s24, 2
	s_add_u32 s8, s0, 0x100
	s_addc_u32 s9, s1, 0
	s_add_i32 s34, 0, 0x10000
	s_cmp_eq_u32 s13, s24
	s_cselect_b32 s39, s87, s9
	s_cselect_b32 s38, s86, s8
	v_add_u32_e32 v80, s34, v245
	s_cselect_b32 s41, s49, s17
	s_cselect_b32 s40, s48, s16
	s_add_i32 s24, 0, 0x14000
	ds_read_b128 v[136:139], v80
	ds_read_b128 v[140:143], v80 offset:1024
	ds_read_b128 v[144:147], v80 offset:2048
	ds_read_b128 v[148:151], v80 offset:3072
	v_add_u32_e32 v80, s24, v245
	ds_read_b128 v[152:155], v80
	ds_read_b128 v[156:159], v80 offset:1024
	ds_read_b128 v[160:163], v80 offset:2048
	ds_read_b128 v[164:167], v80 offset:3072
	v_mov_b32_e32 v80, v205
	s_add_u32 s0, s0, s89
	ds_read_b128 v[168:171], v246
	ds_read_b128 v[172:175], v246 offset:1024
	ds_read_b128 v[176:179], v246 offset:2048
	ds_read_b128 v[180:183], v246 offset:3072
	ds_read_b128 v[184:187], v246 offset:4096
	ds_read_b128 v[188:191], v246 offset:5120
	ds_read_b128 v[192:195], v246 offset:6144
	ds_read_b128 v[196:199], v246 offset:7168
	s_addc_u32 s1, s1, s94
	s_add_i32 m0, s20, 0xc000
	s_nop 0
	global_load_lds_dwordx4 v80, s[0:1]
	v_mov_b32_e32 v80, v243
	s_add_i32 m0, s20, 0xe000
	s_nop 0
	global_load_lds_dwordx4 v80, s[0:1]
	s_nop 0
	s_waitcnt vmcnt(8)
	s_waitcnt lgkmcnt(0)
	s_barrier
	s_setprio 1
	s_waitcnt lgkmcnt(0)
	v_mfma_f32_16x16x32_bf16 v[132:135], v[136:139], v[168:171], v[132:135]
	v_mfma_f32_16x16x32_bf16 v[128:131], v[144:147], v[168:171], v[128:131]
	v_mfma_f32_16x16x32_bf16 v[124:127], v[136:139], v[176:179], v[124:127]
	v_mfma_f32_16x16x32_bf16 v[120:123], v[144:147], v[176:179], v[120:123]
	v_mfma_f32_16x16x32_bf16 v[108:111], v[136:139], v[184:187], v[108:111]
	v_mfma_f32_16x16x32_bf16 v[104:107], v[144:147], v[184:187], v[104:107]
	v_mfma_f32_16x16x32_bf16 v[92:95], v[136:139], v[192:195], v[92:95]
	v_mfma_f32_16x16x32_bf16 v[86:89], v[144:147], v[192:195], v[88:91]
	v_mfma_f32_16x16x32_bf16 v[132:135], v[140:143], v[172:175], v[132:135]
	v_mfma_f32_16x16x32_bf16 v[128:131], v[148:151], v[172:175], v[128:131]
	v_mfma_f32_16x16x32_bf16 v[124:127], v[140:143], v[180:183], v[124:127]
	v_mfma_f32_16x16x32_bf16 v[120:123], v[148:151], v[180:183], v[120:123]
	v_mfma_f32_16x16x32_bf16 v[108:111], v[140:143], v[188:191], v[108:111]
	v_mfma_f32_16x16x32_bf16 v[104:107], v[148:151], v[188:191], v[104:107]
	v_mfma_f32_16x16x32_bf16 v[92:95], v[140:143], v[196:199], v[92:95]
	v_mfma_f32_16x16x32_bf16 v[86:89], v[148:151], v[196:199], v[86:89]
	s_setprio 0
	s_setprio 1
	v_mfma_f32_16x16x32_bf16 v[116:119], v[152:155], v[168:171], v[116:119]
	v_mfma_f32_16x16x32_bf16 v[112:115], v[160:163], v[168:171], v[112:115]
	v_mfma_f32_16x16x32_bf16 v[100:103], v[152:155], v[176:179], v[100:103]
	v_mfma_f32_16x16x32_bf16 v[96:99], v[160:163], v[176:179], v[96:99]
	v_mfma_f32_16x16x32_bf16 v[76:79], v[152:155], v[184:187], v[76:79]
	v_mfma_f32_16x16x32_bf16 v[72:75], v[160:163], v[184:187], v[72:75]
	v_mfma_f32_16x16x32_bf16 v[68:71], v[152:155], v[192:195], v[68:71]
	v_mfma_f32_16x16x32_bf16 v[60:63], v[160:163], v[192:195], v[60:63]
	v_mfma_f32_16x16x32_bf16 v[116:119], v[156:159], v[172:175], v[116:119]
	v_mfma_f32_16x16x32_bf16 v[112:115], v[164:167], v[172:175], v[112:115]
	v_mfma_f32_16x16x32_bf16 v[100:103], v[156:159], v[180:183], v[100:103]
	v_mfma_f32_16x16x32_bf16 v[96:99], v[164:167], v[180:183], v[96:99]
	v_mfma_f32_16x16x32_bf16 v[76:79], v[156:159], v[188:191], v[76:79]
	v_mfma_f32_16x16x32_bf16 v[72:75], v[164:167], v[188:191], v[72:75]
	v_mfma_f32_16x16x32_bf16 v[68:71], v[156:159], v[196:199], v[68:71]
	v_mfma_f32_16x16x32_bf16 v[60:63], v[164:167], v[196:199], v[60:63]
	s_setprio 0
	s_barrier
	s_nop 0
	v_mov_b32_e32 v80, v242
	s_add_i32 s0, s34, s23
	ds_read_b128 v[168:171], v246 offset:16384
	ds_read_b128 v[172:175], v246 offset:17408
	ds_read_b128 v[176:179], v246 offset:18432
	ds_read_b128 v[180:183], v246 offset:19456
	ds_read_b128 v[184:187], v246 offset:20480
	ds_read_b128 v[188:191], v246 offset:21504
	ds_read_b128 v[192:195], v246 offset:22528
	ds_read_b128 v[196:199], v246 offset:23552
	s_mov_b32 m0, s0
	s_nop 0
	global_load_lds_dwordx4 v80, s[40:41]
	v_mov_b32_e32 v80, v244
	s_add_i32 m0, s0, 0x2000
	s_add_u32 s0, s40, s74
	global_load_lds_dwordx4 v80, s[40:41]
	s_addc_u32 s1, s41, s75
	v_mov_b32_e32 v80, v242
	s_add_i32 s24, s24, s23
	s_mov_b32 m0, s24
	s_nop 0
	global_load_lds_dwordx4 v80, s[0:1]
	v_mov_b32_e32 v80, v244
	s_add_i32 m0, s24, 0x2000
	s_nop 0
	global_load_lds_dwordx4 v80, s[0:1]
	v_mov_b32_e32 v80, v205
	s_mov_b32 m0, s20
	s_nop 0
	global_load_lds_dwordx4 v80, s[38:39]
	v_mov_b32_e32 v80, v243
	s_mov_b32 m0, s72
	s_nop 0
	global_load_lds_dwordx4 v80, s[38:39]
	s_waitcnt vmcnt(8)
	s_waitcnt lgkmcnt(0)
	s_barrier
	s_setprio 1
	s_waitcnt lgkmcnt(0)
	v_mfma_f32_16x16x32_bf16 v[64:67], v[136:139], v[168:171], v[64:67]
	v_mfma_f32_16x16x32_bf16 v[56:59], v[144:147], v[168:171], v[56:59]
	v_mfma_f32_16x16x32_bf16 v[52:55], v[136:139], v[176:179], v[52:55]
	v_mfma_f32_16x16x32_bf16 v[48:51], v[144:147], v[176:179], v[48:51]
	v_mfma_f32_16x16x32_bf16 v[36:39], v[136:139], v[184:187], v[36:39]
	v_mfma_f32_16x16x32_bf16 v[32:35], v[144:147], v[184:187], v[32:35]
	v_mfma_f32_16x16x32_bf16 v[20:23], v[136:139], v[192:195], v[20:23]
	v_mfma_f32_16x16x32_bf16 v[16:19], v[144:147], v[192:195], v[16:19]
	v_mfma_f32_16x16x32_bf16 v[64:67], v[140:143], v[172:175], v[64:67]
	v_mfma_f32_16x16x32_bf16 v[56:59], v[148:151], v[172:175], v[56:59]
	v_mfma_f32_16x16x32_bf16 v[52:55], v[140:143], v[180:183], v[52:55]
	v_mfma_f32_16x16x32_bf16 v[48:51], v[148:151], v[180:183], v[48:51]
	v_mfma_f32_16x16x32_bf16 v[36:39], v[140:143], v[188:191], v[36:39]
	v_mfma_f32_16x16x32_bf16 v[32:35], v[148:151], v[188:191], v[32:35]
	v_mfma_f32_16x16x32_bf16 v[20:23], v[140:143], v[196:199], v[20:23]
	v_mfma_f32_16x16x32_bf16 v[16:19], v[148:151], v[196:199], v[16:19]
	s_setprio 0
	s_setprio 1
	v_mfma_f32_16x16x32_bf16 v[44:47], v[152:155], v[168:171], v[44:47]
	v_mfma_f32_16x16x32_bf16 v[40:43], v[160:163], v[168:171], v[40:43]
	v_mfma_f32_16x16x32_bf16 v[28:31], v[152:155], v[176:179], v[28:31]
	v_mfma_f32_16x16x32_bf16 v[24:27], v[160:163], v[176:179], v[24:27]
	v_mfma_f32_16x16x32_bf16 v[12:15], v[152:155], v[184:187], v[12:15]
	v_mfma_f32_16x16x32_bf16 v[8:11], v[160:163], v[184:187], v[8:11]
	v_mfma_f32_16x16x32_bf16 v[4:7], v[152:155], v[192:195], v[4:7]
	v_mfma_f32_16x16x32_bf16 v[0:3], v[160:163], v[192:195], v[0:3]
	v_mfma_f32_16x16x32_bf16 v[44:47], v[156:159], v[172:175], v[44:47]
	v_mfma_f32_16x16x32_bf16 v[40:43], v[164:167], v[172:175], v[40:43]
	v_mfma_f32_16x16x32_bf16 v[28:31], v[156:159], v[180:183], v[28:31]
	v_mfma_f32_16x16x32_bf16 v[24:27], v[164:167], v[180:183], v[24:27]
	v_mfma_f32_16x16x32_bf16 v[12:15], v[156:159], v[188:191], v[12:15]
	v_mfma_f32_16x16x32_bf16 v[8:11], v[164:167], v[188:191], v[8:11]
	v_mfma_f32_16x16x32_bf16 v[4:7], v[156:159], v[196:199], v[4:7]
	v_mfma_f32_16x16x32_bf16 v[0:3], v[164:167], v[196:199], v[0:3]
	s_setprio 0
	s_barrier
